# speedup vs baseline: 1.1019x; 1.0034x over previous
; __device__ __forceinline__ void phase_prep(const Params& p, char* smem) {
;   const int nblk = gridDim.x, bid = blockIdx.x, tid = threadIdx.x;
;   if (bid == 0 && tid < 64) ((unsigned*)(p.ws + OFF_ZERO))[tid] = 0u;
; __global__ void __launch_bounds__(256, 2) mega(Params p) {
;   extern __shared__ __attribute__((aligned(16))) char smem[];
;   cg::grid_group grid = cg::this_grid();
_Z4mega6Params:
	s_mov_b32 s96, s2
	s_mov_b32 s98, s2
	s_add_u32 s2, s0, 0xf0
	s_addc_u32 s3, s1, 0
	s_load_dwordx16 s[36:51], s[0:1], 0x0
	s_load_dwordx8 s[20:27], s[0:1], 0xc0
	v_writelane_b32 v225, s2, 0
	s_cmp_eq_u32 s96, 0
	v_and_b32_e32 v140, 0x3ff, v0
	v_writelane_b32 v225, s3, 1
	s_load_dwordx4 s[28:31], s[0:1], 0xe0
	s_load_dword s2, s[0:1], 0xf0
	v_cmp_gt_u32_e32 vcc, 64, v140
	v_mov_b32_e32 v141, 0
	v_lshlrev_b32_e32 v144, 2, v140
	s_waitcnt lgkmcnt(0)
	s_mov_b32 s99, s2
	v_writelane_b32 v225, s2, 2
	s_nop 1
	v_writelane_b32 v225, s3, 3
	s_cselect_b64 s[2:3], -1, 0
	s_and_b64 s[2:3], s[2:3], vcc
	s_and_saveexec_b64 s[4:5], s[2:3]
	s_cbranch_execz .LBB0_2
	v_mov_b32_e32 v145, v141
	v_lshl_add_u64 v[2:3], s[30:31], 0, v[144:145]
	v_add_co_u32_e32 v2, vcc, 0x3eb40000, v2
	s_nop 1
	v_addc_co_u32_e32 v3, vcc, 0, v3, vcc
	global_store_dword v[2:3], v141, off
	v_lshlrev_b32_e32 v4, 8, v140
	v_add_u32_e32 v4, 0x3eb38000, v4
	global_store_dword v4, v141, s[30:31]
	s_waitcnt vmcnt(0)
	buffer_wbl2 sc1
	s_waitcnt vmcnt(0)
	v_mov_b32_e32 v5, 0x5eedb0b1
	v_mov_b32_e32 v4, 0x3eb38080
	global_atomic_swap v4, v5, s[30:31]

; #define RUNPH(n) { run_phase(p, (n), smem); grid.sync(); }
; __global__ void __launch_bounds__(256, 2) mega(Params p) {
;   extern __shared__ __attribute__((aligned(16))) char smem[];
;   cg::grid_group grid = cg::this_grid();
;   RUNPH(0) RUNPH(1) RUNPH(2) RUNPH(3) RUNPH(4) RUNPH(5) RUNPH(6) RUNPH(7) RUNPH(8)
.LBB0_109:
	v_lshrrev_b32_e32 v1, 20, v0
	v_lshrrev_b32_e32 v0, 10, v0
	v_or_b32_e32 v0, v0, v1
	s_movk_i32 s0, 0x3ff
	v_and_or_b32 v0, v0, s0, v140
	s_waitcnt vmcnt(0) lgkmcnt(0)
	s_barrier
	v_cmp_eq_u32_e64 s[0:1], 0, v0
	s_mov_b64 s[4:5], exec
	s_nop 0
	v_writelane_b32 v225, s0, 14
	s_nop 1
	v_writelane_b32 v225, s1, 15
	s_and_b64 s[0:1], s[4:5], s[0:1]
	s_mov_b64 exec, s[0:1]
	s_cbranch_execz .LBB0_119
	v_mov_b32_e32 v0, 0
	s_add_u32 s6, s30, 0x3eb38000
	s_addc_u32 s7, s31, 0
	s_mov_b32 s8, 0
.Lgb0_flag:
	global_load_dword v3, v0, s[6:7] offset:128 sc1
	s_add_u32 s8, s8, 1
	s_waitcnt vmcnt(0)
	v_readfirstlane_b32 s0, v3
	s_cmp_eq_u32 s0, 0x5eedb0b1
	s_cbranch_scc1 .Lgb0_go
	s_sleep 1
	s_cmp_lt_u32 s8, 0x40000
	s_cbranch_scc1 .Lgb0_flag
.Lgb0_go:
	buffer_wbl2 sc1
	s_waitcnt vmcnt(0)
	s_and_b32 s0, s98, 7
	s_sub_u32 s1, s99, s0
	s_add_u32 s1, s1, 7
	s_lshr_b32 s1, s1, 3
	s_lshl_b32 s0, s0, 8
	v_mov_b32_e32 v2, s0
	v_mov_b32_e32 v0, 0
	v_mov_b32_e32 v1, 1
	s_mov_b32 s8, 0
	global_atomic_add v3, v2, v1, s[6:7] sc0
	s_waitcnt vmcnt(0)
	v_readfirstlane_b32 s0, v3
	s_add_u32 s0, s0, 1
	s_cmp_eq_u32 s0, s1
	s_cbranch_scc0 .Lgb0_pollg
	s_add_u32 s6, s6, 0x1000
	s_addc_u32 s7, s7, 0
	global_atomic_add v3, v0, v1, s[6:7] sc0
	s_min_u32 s1, s99, 8
	s_waitcnt vmcnt(0)
	v_readfirstlane_b32 s0, v3
	s_add_u32 s0, s0, 1
	s_cmp_eq_u32 s0, s1
	s_cbranch_scc0 .Lgb0_pollt
	global_atomic_add v0, v1, s[6:7] offset:256
	s_branch .Lgb0_relg

; __device__ __forceinline__ ushort_t* wsb(const Params& p, size_t off) { return (ushort_t*)(p.ws + off); }
; __device__ __forceinline__ ushort_t* wts(const Params& p, size_t eoff) { return (ushort_t*)(p.ws + OFF_W) + eoff; }
; __device__ __forceinline__ int opaque_tid() { int t = threadIdx.x; asm volatile("" : "+v"(t)); return t; }
; #define TILE_LOOP2(NTV) for (int q_ = blockIdx.x >> 3, mt = 0, nt = 0; tile_coords(q_, (NTV), mt, nt, 256); q_ += gridDim.x >> 3)
; __device__ __forceinline__ void phase_fox_inproj(const Params& p, char* smem) {
;   const int tid = opaque_tid(), row = tid >> 1, hf = tid & 1;
;   float* Cs = (float*)smem;
;   const ushort_t* xb = wsb(p, OFF_XB);
;   ushort_t* Qb = wsb(p, OFF_P + 0 * SLOT);
;   ushort_t* Kb = wsb(p, OFF_P + 1 * SLOT);
;   ushort_t* Vt = wsb(p, OFF_P + 2 * SLOT);
;   ushort_t* G = wsb(p, OFF_P + 3 * SLOT);
;   float* LF = (float*)(p.ws + OFF_LF);
;   const int NT = 33;
;   TILE_LOOP2(NT) {
;     f32x4 acc[8][4];
;     gemm_core256<false>(xb + (long)mt * 256 * 1024, 1024, wts(p, W_FOX_IN) + (long)nt * 128 * 1024, 1024, 1024, smem, acc, mt * 256, wsb(p, OFF_ZERO));
.Lgb0_done:
	buffer_inv sc1
	s_waitcnt vmcnt(0)
.LBB0_119:
	s_or_b64 exec, exec, s[4:5]
	s_add_u32 s48, s30, 0x30000000
	s_addc_u32 s49, s31, 0
	s_add_u32 s46, s30, 0x10000000
	s_addc_u32 s47, s31, 0
	s_add_u32 s16, s30, 0x3b740000
	v_mov_b32_e32 v0, v140
	s_addc_u32 s17, s31, 0
	s_lshr_b32 s94, s96, 3
	s_and_b32 s93, s96, 7
	s_barrier
	s_add_u32 s1, s30, 0x38000000
	v_ashrrev_i32_e32 v143, 1, v0
	v_lshlrev_b32_e32 v0, 2, v0
	v_writelane_b32 v225, s1, 18
	s_addc_u32 s1, s31, 0
	v_and_b32_e32 v145, 4, v0
	s_movk_i32 s0, 0x210
	v_writelane_b32 v225, s1, 13
	v_mul_lo_u32 v1, v143, s0
	v_lshlrev_b32_e32 v0, 2, v145
	v_readlane_b32 s2, v225, 2
	s_mov_b32 s5, 0
	v_add3_u32 v154, 0, v1, v0
	v_mov_b32_e32 v1, 0
	v_readlane_b32 s3, v225, 3
	v_or_b32_e32 v155, 1, v145
	v_or_b32_e32 v156, 2, v145
	v_or_b32_e32 v157, 3, v145
	v_lshl_add_u64 v[136:137], s[44:45], 0, v[0:1]
	s_lshr_b32 s95, s2, 3
	s_movk_i32 s1, 0xf800
	s_mov_b64 s[6:7], 0x20000
	s_mov_b64 s[8:9], 0x20040
	s_add_i32 s33, 0, 0x10000
	s_movk_i32 s3, 0x84
	s_mov_b32 s23, 0xbfb8aa3b
	s_mov_b32 s35, 0x3f2aaaab
	v_mov_b32_e32 v158, 0x3ecc95a3
	s_mov_b32 s82, 0x3f317218
	s_mov_b32 s83, 0x7f800000
	s_mov_b32 s84, 0x33800000
	s_mov_b32 s85, 0x20000
	v_mov_b32_e32 v159, 0x7f800000
	v_mov_b32_e32 v160, 0x7fc00000
	v_mov_b32_e32 v161, 0xff800000
	s_mov_b32 s86, s94
	s_mov_b64 s[10:11], 0x30020100
	s_mov_b64 s[12:13], 0x30040100
	s_mov_b64 s[14:15], 0x30060100
	s_mov_b64 s[18:19], 0x38000100
	s_mov_b64 s[20:21], 0x38020100
	s_mov_b32 s22, 0x3e0293ee
	s_mov_b32 s26, s5
	s_mov_b32 s42, s5
	s_branch .LBB0_122

; #define RUNPH(n) { run_phase(p, (n), smem); grid.sync(); }
; __global__ void __launch_bounds__(256, 2) mega(Params p) {
;   extern __shared__ __attribute__((aligned(16))) char smem[];
;   cg::grid_group grid = cg::this_grid();
;   RUNPH(0) RUNPH(1) RUNPH(2) RUNPH(3) RUNPH(4) RUNPH(5) RUNPH(6) RUNPH(7) RUNPH(8)
;   RUNPH(18) RUNPH(19) RUNPH(9)
;   RUNPH(10) RUNPH(11) RUNPH(12) RUNPH(13) RUNPH(14) RUNPH(15) RUNPH(16)
.LBB0_169:
	s_waitcnt vmcnt(0)
	s_barrier
	s_mov_b64 s[4:5], exec
	v_readlane_b32 s0, v225, 14
	v_readlane_b32 s1, v225, 15
	s_and_b64 s[0:1], s[4:5], s[0:1]
	s_mov_b64 exec, s[0:1]
	s_cbranch_execz .LBB0_179
	s_getreg_b32 s0, hwreg(HW_REG_XCC_ID, 0, 4)
	s_and_b32 s0, s0, 15
	s_lshl_b32 s0, 1, s0
	s_and_b32 s1, s98, 7
	s_lshl_b32 s1, s1, 8
	s_mov_b32 s100, 0
	v_mov_b32_e32 v0, s1
	v_mov_b32_e32 v1, s0
	s_add_u32 s6, s30, 0x3eb3a000
	s_addc_u32 s7, s31, 0
	global_atomic_or v0, v1, s[6:7]
	buffer_wbl2 sc1
	s_waitcnt vmcnt(0)
	s_and_b32 s0, s98, 7
	s_sub_u32 s1, s99, s0
	s_add_u32 s1, s1, 7
	s_lshr_b32 s1, s1, 3
	s_mul_i32 s1, s1, 2
	s_lshl_b32 s0, s0, 8
	v_mov_b32_e32 v2, s0
	v_mov_b32_e32 v0, 0
	v_mov_b32_e32 v1, 1
	s_add_u32 s6, s30, 0x3eb38000
	s_addc_u32 s7, s31, 0
	s_mov_b32 s8, 0
	global_atomic_add v3, v2, v1, s[6:7] sc0
	s_waitcnt vmcnt(0)
	v_readfirstlane_b32 s0, v3
	s_add_u32 s0, s0, 1
	s_cmp_eq_u32 s0, s1
	s_cbranch_scc0 .Lgb1_pollg
	s_add_u32 s6, s6, 0x1000
	s_addc_u32 s7, s7, 0
	global_atomic_add v3, v0, v1, s[6:7] sc0
	s_min_u32 s1, s99, 8
	s_mul_i32 s1, s1, 2
	s_waitcnt vmcnt(0)
	v_readfirstlane_b32 s0, v3
	s_add_u32 s0, s0, 1
	s_cmp_eq_u32 s0, s1
	s_cbranch_scc0 .Lgb1_pollt
	global_atomic_add v0, v1, s[6:7] offset:256
	s_branch .Lgb1_relg

; #define RUNPH(n) { run_phase(p, (n), smem); grid.sync(); }
; __global__ void __launch_bounds__(256, 2) mega(Params p) {
;   extern __shared__ __attribute__((aligned(16))) char smem[];
;   cg::grid_group grid = cg::this_grid();
;   RUNPH(0) RUNPH(1) RUNPH(2) RUNPH(3) RUNPH(4) RUNPH(5) RUNPH(6) RUNPH(7) RUNPH(8)
;   RUNPH(18) RUNPH(19) RUNPH(9)
;   RUNPH(10) RUNPH(11) RUNPH(12) RUNPH(13) RUNPH(14) RUNPH(15) RUNPH(16)
.Lgb1_done:
	s_cmp_lg_u32 s98, 0
	s_cbranch_scc1 .Lgb1_norst
	s_add_u32 s6, s30, 0x3eb38000
	s_addc_u32 s7, s31, 0
	v_mov_b32_e32 v0, 0
	v_mov_b32_e32 v1, 0
	global_atomic_swap v0, v1, s[6:7] offset:128

; #define RUNPH(n) { run_phase(p, (n), smem); grid.sync(); }
; __global__ void __launch_bounds__(256, 2) mega(Params p) {
;   extern __shared__ __attribute__((aligned(16))) char smem[];
;   cg::grid_group grid = cg::this_grid();
;   RUNPH(0) RUNPH(1) RUNPH(2) RUNPH(3) RUNPH(4) RUNPH(5) RUNPH(6) RUNPH(7) RUNPH(8)
;   RUNPH(18) RUNPH(19) RUNPH(9)
;   RUNPH(10) RUNPH(11) RUNPH(12) RUNPH(13) RUNPH(14) RUNPH(15) RUNPH(16)
.LBB0_182:
	s_or_b64 exec, exec, s[18:19]
	s_waitcnt vmcnt(0)
	s_barrier
	s_mov_b64 s[4:5], exec
	v_readlane_b32 s0, v225, 14
	v_readlane_b32 s1, v225, 15
	s_and_b64 s[0:1], s[4:5], s[0:1]
	s_mov_b64 exec, s[0:1]
	s_cbranch_execz .LBB0_192
	s_cmp_eq_u32 s100, 1
	s_cbranch_scc1 .Lgb2_nowb
	buffer_wbl2 sc1
	s_waitcnt vmcnt(0)
.Lgb2_nowb:
	s_and_b32 s0, s98, 7
	s_sub_u32 s1, s99, s0
	s_add_u32 s1, s1, 7
	s_lshr_b32 s1, s1, 3
	s_mul_i32 s1, s1, 3
	s_lshl_b32 s0, s0, 8
	v_mov_b32_e32 v2, s0
	v_mov_b32_e32 v0, 0
	v_mov_b32_e32 v1, 1
	s_add_u32 s6, s30, 0x3eb38000
	s_addc_u32 s7, s31, 0
	s_mov_b32 s8, 0
	global_atomic_add v3, v2, v1, s[6:7] sc0
	s_waitcnt vmcnt(0)
	v_readfirstlane_b32 s0, v3
	s_add_u32 s0, s0, 1
	s_cmp_eq_u32 s0, s1
	s_cbranch_scc0 .Lgb2_pollg
	buffer_wbl2 sc1
	s_waitcnt vmcnt(0)
	s_add_u32 s6, s6, 0x1000
	s_addc_u32 s7, s7, 0
	global_atomic_add v3, v0, v1, s[6:7] sc0
	s_min_u32 s1, s99, 8
	s_mul_i32 s1, s1, 3
	s_waitcnt vmcnt(0)
	v_readfirstlane_b32 s0, v3
	s_add_u32 s0, s0, 1
	s_cmp_eq_u32 s0, s1
	s_cbranch_scc0 .Lgb2_pollt
	global_atomic_add v0, v1, s[6:7] offset:256
	s_branch .Lgb2_relg

; #define RUNPH(n) { run_phase(p, (n), smem); grid.sync(); }
; __global__ void __launch_bounds__(256, 2) mega(Params p) {
;   extern __shared__ __attribute__((aligned(16))) char smem[];
;   cg::grid_group grid = cg::this_grid();
;   RUNPH(0) RUNPH(1) RUNPH(2) RUNPH(3) RUNPH(4) RUNPH(5) RUNPH(6) RUNPH(7) RUNPH(8)
;   RUNPH(18) RUNPH(19) RUNPH(9)
;   RUNPH(10) RUNPH(11) RUNPH(12) RUNPH(13) RUNPH(14) RUNPH(15) RUNPH(16)
.LBB0_317:
	s_waitcnt vmcnt(0)
	s_barrier
	s_mov_b64 s[4:5], exec
	v_readlane_b32 s0, v225, 14
	v_readlane_b32 s1, v225, 15
	s_and_b64 s[0:1], s[4:5], s[0:1]
	s_mov_b64 exec, s[0:1]
	s_cbranch_execz .LBB0_327
	s_cmp_eq_u32 s100, 1
	s_cbranch_scc1 .Lgb5_nowb
	buffer_wbl2 sc1
	s_waitcnt vmcnt(0)
.Lgb5_nowb:
	s_and_b32 s0, s98, 7
	s_sub_u32 s1, s99, s0
	s_add_u32 s1, s1, 7
	s_lshr_b32 s1, s1, 3
	s_mul_i32 s1, s1, 6
	s_lshl_b32 s0, s0, 8
	v_mov_b32_e32 v2, s0
	v_mov_b32_e32 v0, 0
	v_mov_b32_e32 v1, 1
	s_add_u32 s6, s30, 0x3eb38000
	s_addc_u32 s7, s31, 0
	s_mov_b32 s8, 0
	global_atomic_add v3, v2, v1, s[6:7] sc0
	s_waitcnt vmcnt(0)
	v_readfirstlane_b32 s0, v3
	s_add_u32 s0, s0, 1
	s_cmp_eq_u32 s0, s1
	s_cbranch_scc0 .Lgb5_pollg
	buffer_wbl2 sc1
	s_waitcnt vmcnt(0)
	s_add_u32 s6, s6, 0x1000
	s_addc_u32 s7, s7, 0
	global_atomic_add v3, v0, v1, s[6:7] sc0
	s_min_u32 s1, s99, 8
	s_mul_i32 s1, s1, 6
	s_waitcnt vmcnt(0)
	v_readfirstlane_b32 s0, v3
	s_add_u32 s0, s0, 1
	s_cmp_eq_u32 s0, s1
	s_cbranch_scc0 .Lgb5_pollt
	global_atomic_add v0, v1, s[6:7] offset:256
	s_branch .Lgb5_relg

; #define RUNPH(n) { run_phase(p, (n), smem); grid.sync(); }
; __global__ void __launch_bounds__(256, 2) mega(Params p) {
;   extern __shared__ __attribute__((aligned(16))) char smem[];
;   cg::grid_group grid = cg::this_grid();
;   RUNPH(0) RUNPH(1) RUNPH(2) RUNPH(3) RUNPH(4) RUNPH(5) RUNPH(6) RUNPH(7) RUNPH(8)
;   RUNPH(18) RUNPH(19) RUNPH(9)
;   RUNPH(10) RUNPH(11) RUNPH(12) RUNPH(13) RUNPH(14) RUNPH(15) RUNPH(16)
.Lgb6_nowb:
	s_and_b32 s0, s98, 7
	s_sub_u32 s1, s99, s0
	s_add_u32 s1, s1, 7
	s_lshr_b32 s1, s1, 3
	s_mul_i32 s1, s1, 7
	s_lshl_b32 s0, s0, 8
	v_mov_b32_e32 v2, s0
	v_mov_b32_e32 v0, 0
	v_mov_b32_e32 v1, 1
	s_add_u32 s6, s30, 0x3eb38000
	s_addc_u32 s7, s31, 0
	s_mov_b32 s8, 0
	global_atomic_add v3, v2, v1, s[6:7] sc0
	s_waitcnt vmcnt(0)
	v_readfirstlane_b32 s0, v3
	s_add_u32 s0, s0, 1
	s_cmp_eq_u32 s0, s1
	s_cbranch_scc0 .Lgb6_pollg
	buffer_wbl2 sc1
	s_waitcnt vmcnt(0)
	s_add_u32 s6, s6, 0x1000
	s_addc_u32 s7, s7, 0
	global_atomic_add v3, v0, v1, s[6:7] sc0
	s_min_u32 s1, s99, 8
	s_mul_i32 s1, s1, 7
	s_waitcnt vmcnt(0)
	v_readfirstlane_b32 s0, v3
	s_add_u32 s0, s0, 1
	s_cmp_eq_u32 s0, s1
	s_cbranch_scc0 .Lgb6_pollt
	global_atomic_add v0, v1, s[6:7] offset:256
	s_branch .Lgb6_relg
.Lgb6_pollt:
	s_sleep 1
	global_load_dword v3, v0, s[6:7] offset:256 sc1
	s_add_u32 s8, s8, 1
	s_waitcnt vmcnt(0)
	v_readfirstlane_b32 s0, v3
	s_cmp_ge_u32 s0, 7
	s_cbranch_scc1 .Lgb6_relg
	s_cmp_lt_u32 s8, 0x40000
	s_cbranch_scc1 .Lgb6_pollt

; #define RUNPH(n) { run_phase(p, (n), smem); grid.sync(); }
; __global__ void __launch_bounds__(256, 2) mega(Params p) {
;   extern __shared__ __attribute__((aligned(16))) char smem[];
;   cg::grid_group grid = cg::this_grid();
;   RUNPH(0) RUNPH(1) RUNPH(2) RUNPH(3) RUNPH(4) RUNPH(5) RUNPH(6) RUNPH(7) RUNPH(8)
;   RUNPH(18) RUNPH(19) RUNPH(9)
;   RUNPH(10) RUNPH(11) RUNPH(12) RUNPH(13) RUNPH(14) RUNPH(15) RUNPH(16)
.Lgb6_pollg:
	s_sleep 1
	global_load_dword v3, v2, s[6:7] offset:2048 sc1
	s_add_u32 s8, s8, 1
	s_waitcnt vmcnt(0)
	v_readfirstlane_b32 s0, v3
	s_cmp_ge_u32 s0, 7
	s_cbranch_scc1 .Lgb6_done
	s_cmp_lt_u32 s8, 0x40000
	s_cbranch_scc1 .Lgb6_pollg

; #define RUNPH(n) { run_phase(p, (n), smem); grid.sync(); }
; __global__ void __launch_bounds__(256, 2) mega(Params p) {
;   extern __shared__ __attribute__((aligned(16))) char smem[];
;   cg::grid_group grid = cg::this_grid();
;   RUNPH(0) RUNPH(1) RUNPH(2) RUNPH(3) RUNPH(4) RUNPH(5) RUNPH(6) RUNPH(7) RUNPH(8)
;   RUNPH(18) RUNPH(19) RUNPH(9)
;   RUNPH(10) RUNPH(11) RUNPH(12) RUNPH(13) RUNPH(14) RUNPH(15) RUNPH(16)
.Lgb7_nowb:
	s_and_b32 s2, s98, 7
	s_sub_u32 s3, s99, s2
	s_add_u32 s3, s3, 7
	s_lshr_b32 s3, s3, 3
	s_mul_i32 s3, s3, 8
	s_lshl_b32 s2, s2, 8
	v_mov_b32_e32 v2, s2
	v_mov_b32_e32 v0, 0
	v_mov_b32_e32 v1, 1
	s_add_u32 s6, s30, 0x3eb38000
	s_addc_u32 s7, s31, 0
	s_mov_b32 s8, 0
	global_atomic_add v3, v2, v1, s[6:7] sc0
	s_waitcnt vmcnt(0)
	v_readfirstlane_b32 s2, v3
	s_add_u32 s2, s2, 1
	s_cmp_eq_u32 s2, s3
	s_cbranch_scc0 .Lgb7_pollg
	buffer_wbl2 sc1
	s_waitcnt vmcnt(0)
	s_add_u32 s6, s6, 0x1000
	s_addc_u32 s7, s7, 0
	global_atomic_add v3, v0, v1, s[6:7] sc0
	s_min_u32 s3, s99, 8
	s_mul_i32 s3, s3, 8
	s_waitcnt vmcnt(0)
	v_readfirstlane_b32 s2, v3
	s_add_u32 s2, s2, 1
	s_cmp_eq_u32 s2, s3
	s_cbranch_scc0 .Lgb7_pollt
	global_atomic_add v0, v1, s[6:7] offset:256
	s_branch .Lgb7_relg
.Lgb7_pollt:
	s_sleep 1
	global_load_dword v3, v0, s[6:7] offset:256 sc1
	s_add_u32 s8, s8, 1
	s_waitcnt vmcnt(0)
	v_readfirstlane_b32 s2, v3
	s_cmp_ge_u32 s2, 8
	s_cbranch_scc1 .Lgb7_relg
	s_cmp_lt_u32 s8, 0x40000
	s_cbranch_scc1 .Lgb7_pollt

; #define RUNPH(n) { run_phase(p, (n), smem); grid.sync(); }
; __global__ void __launch_bounds__(256, 2) mega(Params p) {
;   extern __shared__ __attribute__((aligned(16))) char smem[];
;   cg::grid_group grid = cg::this_grid();
;   RUNPH(0) RUNPH(1) RUNPH(2) RUNPH(3) RUNPH(4) RUNPH(5) RUNPH(6) RUNPH(7) RUNPH(8)
;   RUNPH(18) RUNPH(19) RUNPH(9)
;   RUNPH(10) RUNPH(11) RUNPH(12) RUNPH(13) RUNPH(14) RUNPH(15) RUNPH(16)
.Lgb7_pollg:
	s_sleep 1
	global_load_dword v3, v2, s[6:7] offset:2048 sc1
	s_add_u32 s8, s8, 1
	s_waitcnt vmcnt(0)
	v_readfirstlane_b32 s2, v3
	s_cmp_ge_u32 s2, 8
	s_cbranch_scc1 .Lgb7_done
	s_cmp_lt_u32 s8, 0x40000
	s_cbranch_scc1 .Lgb7_pollg

; #define RUNPH(n) { run_phase(p, (n), smem); grid.sync(); }
; __global__ void __launch_bounds__(256, 2) mega(Params p) {
;   extern __shared__ __attribute__((aligned(16))) char smem[];
;   cg::grid_group grid = cg::this_grid();
;   RUNPH(0) RUNPH(1) RUNPH(2) RUNPH(3) RUNPH(4) RUNPH(5) RUNPH(6) RUNPH(7) RUNPH(8)
;   RUNPH(18) RUNPH(19) RUNPH(9)
;   RUNPH(10) RUNPH(11) RUNPH(12) RUNPH(13) RUNPH(14) RUNPH(15) RUNPH(16)
.Lgb8_nowb:
	s_and_b32 s0, s98, 7
	s_sub_u32 s1, s99, s0
	s_add_u32 s1, s1, 7
	s_lshr_b32 s1, s1, 3
	s_mul_i32 s1, s1, 9
	s_lshl_b32 s0, s0, 8
	v_mov_b32_e32 v2, s0
	v_mov_b32_e32 v0, 0
	v_mov_b32_e32 v1, 1
	s_add_u32 s8, s30, 0x3eb38000
	s_addc_u32 s9, s31, 0
	s_mov_b32 s10, 0
	global_atomic_add v3, v2, v1, s[8:9] sc0
	s_waitcnt vmcnt(0)
	v_readfirstlane_b32 s0, v3
	s_add_u32 s0, s0, 1
	s_cmp_eq_u32 s0, s1
	s_cbranch_scc0 .Lgb8_pollg
	buffer_wbl2 sc1
	s_waitcnt vmcnt(0)
	s_add_u32 s8, s8, 0x1000
	s_addc_u32 s9, s9, 0
	global_atomic_add v3, v0, v1, s[8:9] sc0
	s_min_u32 s1, s99, 8
	s_mul_i32 s1, s1, 9
	s_waitcnt vmcnt(0)
	v_readfirstlane_b32 s0, v3
	s_add_u32 s0, s0, 1
	s_cmp_eq_u32 s0, s1
	s_cbranch_scc0 .Lgb8_pollt
	global_atomic_add v0, v1, s[8:9] offset:256
	s_branch .Lgb8_relg
.Lgb8_pollt:
	s_sleep 1
	global_load_dword v3, v0, s[8:9] offset:256 sc1
	s_add_u32 s10, s10, 1
	s_waitcnt vmcnt(0)
	v_readfirstlane_b32 s0, v3
	s_cmp_ge_u32 s0, 9
	s_cbranch_scc1 .Lgb8_relg
	s_cmp_lt_u32 s10, 0x40000
	s_cbranch_scc1 .Lgb8_pollt

; #define RUNPH(n) { run_phase(p, (n), smem); grid.sync(); }
; __global__ void __launch_bounds__(256, 2) mega(Params p) {
;   extern __shared__ __attribute__((aligned(16))) char smem[];
;   cg::grid_group grid = cg::this_grid();
;   RUNPH(0) RUNPH(1) RUNPH(2) RUNPH(3) RUNPH(4) RUNPH(5) RUNPH(6) RUNPH(7) RUNPH(8)
;   RUNPH(18) RUNPH(19) RUNPH(9)
;   RUNPH(10) RUNPH(11) RUNPH(12) RUNPH(13) RUNPH(14) RUNPH(15) RUNPH(16)
.Lgb8_pollg:
	s_sleep 1
	global_load_dword v3, v2, s[8:9] offset:2048 sc1
	s_add_u32 s10, s10, 1
	s_waitcnt vmcnt(0)
	v_readfirstlane_b32 s0, v3
	s_cmp_ge_u32 s0, 9
	s_cbranch_scc1 .Lgb8_done
	s_cmp_lt_u32 s10, 0x40000
	s_cbranch_scc1 .Lgb8_pollg

; #define RUNPH(n) { run_phase(p, (n), smem); grid.sync(); }
; __global__ void __launch_bounds__(256, 2) mega(Params p) {
;   extern __shared__ __attribute__((aligned(16))) char smem[];
;   cg::grid_group grid = cg::this_grid();
;   RUNPH(0) RUNPH(1) RUNPH(2) RUNPH(3) RUNPH(4) RUNPH(5) RUNPH(6) RUNPH(7) RUNPH(8)
;   RUNPH(18) RUNPH(19) RUNPH(9)
;   RUNPH(10) RUNPH(11) RUNPH(12) RUNPH(13) RUNPH(14) RUNPH(15) RUNPH(16)
.Lgb9_nowb:
	s_and_b32 s0, s98, 7
	s_sub_u32 s1, s99, s0
	s_add_u32 s1, s1, 7
	s_lshr_b32 s1, s1, 3
	s_mul_i32 s1, s1, 10
	s_lshl_b32 s0, s0, 8
	v_mov_b32_e32 v2, s0
	v_mov_b32_e32 v0, 0
	v_mov_b32_e32 v1, 1
	s_add_u32 s8, s30, 0x3eb38000
	s_addc_u32 s9, s31, 0
	s_mov_b32 s12, 0
	global_atomic_add v3, v2, v1, s[8:9] sc0
	s_waitcnt vmcnt(0)
	v_readfirstlane_b32 s0, v3
	s_add_u32 s0, s0, 1
	s_cmp_eq_u32 s0, s1
	s_cbranch_scc0 .Lgb9_pollg
	buffer_wbl2 sc1
	s_waitcnt vmcnt(0)
	s_add_u32 s8, s8, 0x1000
	s_addc_u32 s9, s9, 0
	global_atomic_add v3, v0, v1, s[8:9] sc0
	s_min_u32 s1, s99, 8
	s_mul_i32 s1, s1, 10
	s_waitcnt vmcnt(0)
	v_readfirstlane_b32 s0, v3
	s_add_u32 s0, s0, 1
	s_cmp_eq_u32 s0, s1
	s_cbranch_scc0 .Lgb9_pollt
	global_atomic_add v0, v1, s[8:9] offset:256
	s_branch .Lgb9_relg
.Lgb9_pollt:
	s_sleep 1
	global_load_dword v3, v0, s[8:9] offset:256 sc1
	s_add_u32 s12, s12, 1
	s_waitcnt vmcnt(0)
	v_readfirstlane_b32 s0, v3
	s_cmp_ge_u32 s0, 10
	s_cbranch_scc1 .Lgb9_relg
	s_cmp_lt_u32 s12, 0x40000
	s_cbranch_scc1 .Lgb9_pollt

; #define RUNPH(n) { run_phase(p, (n), smem); grid.sync(); }
; __global__ void __launch_bounds__(256, 2) mega(Params p) {
;   extern __shared__ __attribute__((aligned(16))) char smem[];
;   cg::grid_group grid = cg::this_grid();
;   RUNPH(0) RUNPH(1) RUNPH(2) RUNPH(3) RUNPH(4) RUNPH(5) RUNPH(6) RUNPH(7) RUNPH(8)
;   RUNPH(18) RUNPH(19) RUNPH(9)
;   RUNPH(10) RUNPH(11) RUNPH(12) RUNPH(13) RUNPH(14) RUNPH(15) RUNPH(16)
.Lgb9_pollg:
	s_sleep 1
	global_load_dword v3, v2, s[8:9] offset:2048 sc1
	s_add_u32 s12, s12, 1
	s_waitcnt vmcnt(0)
	v_readfirstlane_b32 s0, v3
	s_cmp_ge_u32 s0, 10
	s_cbranch_scc1 .Lgb9_done
	s_cmp_lt_u32 s12, 0x40000
	s_cbranch_scc1 .Lgb9_pollg

; #define RUNPH(n) { run_phase(p, (n), smem); grid.sync(); }
; __global__ void __launch_bounds__(256, 2) mega(Params p) {
;   extern __shared__ __attribute__((aligned(16))) char smem[];
;   cg::grid_group grid = cg::this_grid();
;   RUNPH(0) RUNPH(1) RUNPH(2) RUNPH(3) RUNPH(4) RUNPH(5) RUNPH(6) RUNPH(7) RUNPH(8)
;   RUNPH(18) RUNPH(19) RUNPH(9)
;   RUNPH(10) RUNPH(11) RUNPH(12) RUNPH(13) RUNPH(14) RUNPH(15) RUNPH(16)
.Lgb10_nowb:
	s_and_b32 s0, s98, 7
	s_sub_u32 s1, s99, s0
	s_add_u32 s1, s1, 7
	s_lshr_b32 s1, s1, 3
	s_mul_i32 s1, s1, 11
	s_lshl_b32 s0, s0, 8
	v_mov_b32_e32 v2, s0
	v_mov_b32_e32 v0, 0
	v_mov_b32_e32 v1, 1
	s_add_u32 s14, s30, 0x3eb38000
	s_addc_u32 s15, s31, 0
	s_mov_b32 s16, 0
	global_atomic_add v3, v2, v1, s[14:15] sc0
	s_waitcnt vmcnt(0)
	v_readfirstlane_b32 s0, v3
	s_add_u32 s0, s0, 1
	s_cmp_eq_u32 s0, s1
	s_cbranch_scc0 .Lgb10_pollg
	buffer_wbl2 sc1
	s_waitcnt vmcnt(0)
	s_add_u32 s14, s14, 0x1000
	s_addc_u32 s15, s15, 0
	global_atomic_add v3, v0, v1, s[14:15] sc0
	s_min_u32 s1, s99, 8
	s_mul_i32 s1, s1, 11
	s_waitcnt vmcnt(0)
	v_readfirstlane_b32 s0, v3
	s_add_u32 s0, s0, 1
	s_cmp_eq_u32 s0, s1
	s_cbranch_scc0 .Lgb10_pollt
	global_atomic_add v0, v1, s[14:15] offset:256
	s_branch .Lgb10_relg
.Lgb10_pollt:
	s_sleep 1
	global_load_dword v3, v0, s[14:15] offset:256 sc1
	s_add_u32 s16, s16, 1
	s_waitcnt vmcnt(0)
	v_readfirstlane_b32 s0, v3
	s_cmp_ge_u32 s0, 11
	s_cbranch_scc1 .Lgb10_relg
	s_cmp_lt_u32 s16, 0x40000
	s_cbranch_scc1 .Lgb10_pollt

; #define RUNPH(n) { run_phase(p, (n), smem); grid.sync(); }
; __global__ void __launch_bounds__(256, 2) mega(Params p) {
;     ...
;   RUNPH(0) RUNPH(1) RUNPH(2) RUNPH(3) RUNPH(4) RUNPH(5) RUNPH(6) RUNPH(7) RUNPH(8)
;   RUNPH(18) RUNPH(19) RUNPH(9)
.Lgb10_pollg:
	s_sleep 1
	global_load_dword v3, v2, s[14:15] offset:2048 sc1
	s_add_u32 s16, s16, 1
	s_waitcnt vmcnt(0)
	v_readfirstlane_b32 s0, v3
	s_cmp_ge_u32 s0, 11
	s_cbranch_scc1 .Lgb10_done
	s_cmp_lt_u32 s16, 0x40000
	s_cbranch_scc1 .Lgb10_pollg

; #define RUNPH(n) { run_phase(p, (n), smem); grid.sync(); }
; __global__ void __launch_bounds__(256, 2) mega(Params p) {
;     ...
;   RUNPH(0) RUNPH(1) RUNPH(2) RUNPH(3) RUNPH(4) RUNPH(5) RUNPH(6) RUNPH(7) RUNPH(8)
;   RUNPH(18) RUNPH(19) RUNPH(9)
.LBB0_1481:
	s_waitcnt vmcnt(0)
	s_barrier
	s_mov_b64 s[6:7], exec
	v_readlane_b32 s0, v225, 14
	v_readlane_b32 s1, v225, 15
	v_readlane_b32 s74, v225, 4
	s_and_b64 s[0:1], s[6:7], s[0:1]
	v_readlane_b32 s75, v225, 5
	v_readlane_b32 s92, v225, 16
	s_mov_b64 exec, s[0:1]
	s_cbranch_execz .LBB0_1491
	s_cmp_eq_u32 s100, 1
	s_cbranch_scc1 .Lgb11_nowb
	buffer_wbl2 sc1
	s_waitcnt vmcnt(0)
.Lgb11_nowb:
	s_and_b32 s0, s98, 7
	s_sub_u32 s1, s99, s0
	s_add_u32 s1, s1, 7
	s_lshr_b32 s1, s1, 3
	s_mul_i32 s1, s1, 12
	s_lshl_b32 s0, s0, 8
	v_mov_b32_e32 v2, s0
	v_mov_b32_e32 v0, 0
	v_mov_b32_e32 v1, 1
	s_add_u32 s8, s30, 0x3eb38000
	s_addc_u32 s9, s31, 0
	s_mov_b32 s12, 0
	global_atomic_add v3, v2, v1, s[8:9] sc0
	s_waitcnt vmcnt(0)
	v_readfirstlane_b32 s0, v3
	s_add_u32 s0, s0, 1
	s_cmp_eq_u32 s0, s1
	s_cbranch_scc0 .Lgb11_pollg
	buffer_wbl2 sc1
	s_waitcnt vmcnt(0)
	s_add_u32 s8, s8, 0x1000
	s_addc_u32 s9, s9, 0
	global_atomic_add v3, v0, v1, s[8:9] sc0
	s_min_u32 s1, s99, 8
	s_mul_i32 s1, s1, 12
	s_waitcnt vmcnt(0)
	v_readfirstlane_b32 s0, v3
	s_add_u32 s0, s0, 1
	s_cmp_eq_u32 s0, s1
	s_cbranch_scc0 .Lgb11_pollt
	global_atomic_add v0, v1, s[8:9] offset:256
	s_branch .Lgb11_relg

; #define RUNPH(n) { run_phase(p, (n), smem); grid.sync(); }
; __global__ void __launch_bounds__(256, 2) mega(Params p) {
;     ...
;   RUNPH(18) RUNPH(19) RUNPH(9)
;   RUNPH(10) RUNPH(11) RUNPH(12) RUNPH(13) RUNPH(14) RUNPH(15) RUNPH(16)
.LBB0_1498:
	s_waitcnt vmcnt(0)
	s_barrier
	s_mov_b64 s[6:7], exec
	v_readlane_b32 s0, v225, 14
	v_readlane_b32 s1, v225, 15
	s_and_b64 s[0:1], s[6:7], s[0:1]
	v_readlane_b32 s96, v225, 2
	v_readlane_b32 s97, v225, 3
	s_mov_b64 exec, s[0:1]
	s_cbranch_execz .LBB0_1508
	s_cmp_eq_u32 s100, 1
	s_cbranch_scc1 .Lgb12_nowb
	buffer_wbl2 sc1
	s_waitcnt vmcnt(0)
.Lgb12_nowb:
	s_and_b32 s0, s98, 7
	s_sub_u32 s1, s99, s0
	s_add_u32 s1, s1, 7
	s_lshr_b32 s1, s1, 3
	s_mul_i32 s1, s1, 13
	s_lshl_b32 s0, s0, 8
	v_mov_b32_e32 v2, s0
	v_mov_b32_e32 v0, 0
	v_mov_b32_e32 v1, 1
	s_add_u32 s8, s30, 0x3eb38000
	s_addc_u32 s9, s31, 0
	s_mov_b32 s12, 0
	global_atomic_add v3, v2, v1, s[8:9] sc0
	s_waitcnt vmcnt(0)
	v_readfirstlane_b32 s0, v3
	s_add_u32 s0, s0, 1
	s_cmp_eq_u32 s0, s1
	s_cbranch_scc0 .Lgb12_pollg
	buffer_wbl2 sc1
	s_waitcnt vmcnt(0)
	s_add_u32 s8, s8, 0x1000
	s_addc_u32 s9, s9, 0
	global_atomic_add v3, v0, v1, s[8:9] sc0
	s_min_u32 s1, s99, 8
	s_mul_i32 s1, s1, 13
	s_waitcnt vmcnt(0)
	v_readfirstlane_b32 s0, v3
	s_add_u32 s0, s0, 1
	s_cmp_eq_u32 s0, s1
	s_cbranch_scc0 .Lgb12_pollt
	global_atomic_add v0, v1, s[8:9] offset:256
	s_branch .Lgb12_relg

; #define RUNPH(n) { run_phase(p, (n), smem); grid.sync(); }
; __global__ void __launch_bounds__(256, 2) mega(Params p) {
;     ...
;   RUNPH(18) RUNPH(19) RUNPH(9)
;   RUNPH(10) RUNPH(11) RUNPH(12) RUNPH(13) RUNPH(14) RUNPH(15) RUNPH(16)
.LBB0_1644:
	s_waitcnt vmcnt(0)
	s_barrier
	s_mov_b64 s[6:7], exec
	v_readlane_b32 s0, v225, 14
	v_readlane_b32 s1, v225, 15
	s_and_b64 s[0:1], s[6:7], s[0:1]
	s_mov_b64 exec, s[0:1]
	s_cbranch_execz .LBB0_1654
	s_cmp_eq_u32 s100, 1
	s_cbranch_scc1 .Lgb16_nowb
	buffer_wbl2 sc1
	s_waitcnt vmcnt(0)
.Lgb16_nowb:
	s_and_b32 s0, s98, 7
	s_sub_u32 s1, s99, s0
	s_add_u32 s1, s1, 7
	s_lshr_b32 s1, s1, 3
	s_mul_i32 s1, s1, 17
	s_lshl_b32 s0, s0, 8
	v_mov_b32_e32 v2, s0
	v_mov_b32_e32 v0, 0
	v_mov_b32_e32 v1, 1
	s_add_u32 s8, s30, 0x3eb38000
	s_addc_u32 s9, s31, 0
	s_mov_b32 s12, 0
	global_atomic_add v3, v2, v1, s[8:9] sc0
	s_waitcnt vmcnt(0)
	v_readfirstlane_b32 s0, v3
	s_add_u32 s0, s0, 1
	s_cmp_eq_u32 s0, s1
	s_cbranch_scc0 .Lgb16_pollg
	buffer_wbl2 sc1
	s_waitcnt vmcnt(0)
	s_add_u32 s8, s8, 0x1000
	s_addc_u32 s9, s9, 0
	global_atomic_add v3, v0, v1, s[8:9] sc0
	s_min_u32 s1, s99, 8
	s_mul_i32 s1, s1, 17
	s_waitcnt vmcnt(0)
	v_readfirstlane_b32 s0, v3
	s_add_u32 s0, s0, 1
	s_cmp_eq_u32 s0, s1
	s_cbranch_scc0 .Lgb16_pollt
	global_atomic_add v0, v1, s[8:9] offset:256
	s_branch .Lgb16_relg

; #define RUNPH(n) { run_phase(p, (n), smem); grid.sync(); }
; __global__ void __launch_bounds__(256, 2) mega(Params p) {
;     ...
;   RUNPH(18) RUNPH(19) RUNPH(9)
;   RUNPH(10) RUNPH(11) RUNPH(12) RUNPH(13) RUNPH(14) RUNPH(15) RUNPH(16)
.Lgb17_nowb:
	s_and_b32 s0, s98, 7
	s_sub_u32 s1, s99, s0
	s_add_u32 s1, s1, 7
	s_lshr_b32 s1, s1, 3
	s_mul_i32 s1, s1, 18
	s_lshl_b32 s0, s0, 8
	v_mov_b32_e32 v2, s0
	v_mov_b32_e32 v0, 0
	v_mov_b32_e32 v1, 1
	s_add_u32 s8, s30, 0x3eb38000
	s_addc_u32 s9, s31, 0
	s_mov_b32 s12, 0
	global_atomic_add v3, v2, v1, s[8:9] sc0
	s_waitcnt vmcnt(0)
	v_readfirstlane_b32 s0, v3
	s_add_u32 s0, s0, 1
	s_cmp_eq_u32 s0, s1
	s_cbranch_scc0 .Lgb17_pollg
	buffer_wbl2 sc1
	s_waitcnt vmcnt(0)
	s_add_u32 s8, s8, 0x1000
	s_addc_u32 s9, s9, 0
	global_atomic_add v3, v0, v1, s[8:9] sc0
	s_min_u32 s1, s99, 8
	s_mul_i32 s1, s1, 18
	s_waitcnt vmcnt(0)
	v_readfirstlane_b32 s0, v3
	s_add_u32 s0, s0, 1
	s_cmp_eq_u32 s0, s1
	s_cbranch_scc0 .Lgb17_pollt
	global_atomic_add v0, v1, s[8:9] offset:256
	s_branch .Lgb17_relg
.Lgb17_pollt:
	s_sleep 1
	global_load_dword v3, v0, s[8:9] offset:256 sc1
	s_add_u32 s12, s12, 1
	s_waitcnt vmcnt(0)
	v_readfirstlane_b32 s0, v3
	s_cmp_ge_u32 s0, 18
	s_cbranch_scc1 .Lgb17_relg
	s_cmp_lt_u32 s12, 0x40000
	s_cbranch_scc1 .Lgb17_pollt

; #define RUNPH(n) { run_phase(p, (n), smem); grid.sync(); }
; __global__ void __launch_bounds__(256, 2) mega(Params p) {
;     ...
;   RUNPH(18) RUNPH(19) RUNPH(9)
;   RUNPH(10) RUNPH(11) RUNPH(12) RUNPH(13) RUNPH(14) RUNPH(15) RUNPH(16)
.Lgb17_pollg:
	s_sleep 1
	global_load_dword v3, v2, s[8:9] offset:2048 sc1
	s_add_u32 s12, s12, 1
	s_waitcnt vmcnt(0)
	v_readfirstlane_b32 s0, v3
	s_cmp_ge_u32 s0, 18
	s_cbranch_scc1 .Lgb17_done
	s_cmp_lt_u32 s12, 0x40000
	s_cbranch_scc1 .Lgb17_pollg

; #define RUNPH(n) { run_phase(p, (n), smem); grid.sync(); }
; __global__ void __launch_bounds__(256, 2) mega(Params p) {
;     ...
;   RUNPH(18) RUNPH(19) RUNPH(9)
;   RUNPH(10) RUNPH(11) RUNPH(12) RUNPH(13) RUNPH(14) RUNPH(15) RUNPH(16)
.Lgb18_nowb:
	s_and_b32 s0, s98, 7
	s_sub_u32 s1, s99, s0
	s_add_u32 s1, s1, 7
	s_lshr_b32 s1, s1, 3
	s_mul_i32 s1, s1, 19
	s_lshl_b32 s0, s0, 8
	v_mov_b32_e32 v2, s0
	v_mov_b32_e32 v0, 0
	v_mov_b32_e32 v1, 1
	s_add_u32 s2, s30, 0x3eb38000
	s_addc_u32 s3, s31, 0
	s_mov_b32 s8, 0
	global_atomic_add v3, v2, v1, s[2:3] sc0
	s_waitcnt vmcnt(0)
	v_readfirstlane_b32 s0, v3
	s_add_u32 s0, s0, 1
	s_cmp_eq_u32 s0, s1
	s_cbranch_scc0 .Lgb18_pollg
	buffer_wbl2 sc1
	s_waitcnt vmcnt(0)
	s_add_u32 s2, s2, 0x1000
	s_addc_u32 s3, s3, 0
	global_atomic_add v3, v0, v1, s[2:3] sc0
	s_min_u32 s1, s99, 8
	s_mul_i32 s1, s1, 19
	s_waitcnt vmcnt(0)
	v_readfirstlane_b32 s0, v3
	s_add_u32 s0, s0, 1
	s_cmp_eq_u32 s0, s1
	s_cbranch_scc0 .Lgb18_pollt
	global_atomic_add v0, v1, s[2:3] offset:256
	s_branch .Lgb18_relg
.Lgb18_pollt:
	s_sleep 1
	global_load_dword v3, v0, s[2:3] offset:256 sc1
	s_add_u32 s8, s8, 1
	s_waitcnt vmcnt(0)
	v_readfirstlane_b32 s0, v3
	s_cmp_ge_u32 s0, 19
	s_cbranch_scc1 .Lgb18_relg
	s_cmp_lt_u32 s8, 0x40000
	s_cbranch_scc1 .Lgb18_pollt

; #define RUNPH(n) { run_phase(p, (n), smem); grid.sync(); }
; __global__ void __launch_bounds__(256, 2) mega(Params p) {
;     ...
;   RUNPH(18) RUNPH(19) RUNPH(9)
;   RUNPH(10) RUNPH(11) RUNPH(12) RUNPH(13) RUNPH(14) RUNPH(15) RUNPH(16)
.Lgb18_pollg:
	s_sleep 1
	global_load_dword v3, v2, s[2:3] offset:2048 sc1
	s_add_u32 s8, s8, 1
	s_waitcnt vmcnt(0)
	v_readfirstlane_b32 s0, v3
	s_cmp_ge_u32 s0, 19
	s_cbranch_scc1 .Lgb18_done
	s_cmp_lt_u32 s8, 0x40000
	s_cbranch_scc1 .Lgb18_pollg
